# A/E GEMM: first K-loop iteration peeled with SrcC=0 on each accumulator's first MFMA; per-unit accumulator zeroing removed; steady-state loop has plain vmcnt(8) waits
# speedup vs baseline: 1.0049x; 1.0049x over previous
.LBB0_394:
	v_readlane_b32 s28, v250, 47
	s_mov_b32 s50, s82
	s_mov_b32 s56, s52
	s_mov_b64 s[54:55], s[58:59]
	s_mov_b32 s29, s46
	s_andn2_b64 vcc, exec, s[20:21]
	s_mov_b64 s[8:9], s[26:27]
	s_cbranch_vccz .LBB0_206

.Lvrp_a1_done:
	s_waitcnt lgkmcnt(0)
	s_barrier
	s_setprio 1
	s_waitcnt lgkmcnt(0)
	v_mfma_f32_16x16x32_bf16 v[128:131], v[136:139], v[168:171], 0
	v_mfma_f32_16x16x32_bf16 v[124:127], v[144:147], v[168:171], 0
	v_mfma_f32_16x16x32_bf16 v[120:123], v[136:139], v[176:179], 0
	v_mfma_f32_16x16x32_bf16 v[116:119], v[144:147], v[176:179], 0
	v_mfma_f32_16x16x32_bf16 v[112:115], v[136:139], v[198:201], 0
	v_mfma_f32_16x16x32_bf16 v[108:111], v[144:147], v[198:201], 0
	v_mfma_f32_16x16x32_bf16 v[104:107], v[136:139], v[216:219], 0
	v_mfma_f32_16x16x32_bf16 v[100:103], v[144:147], v[216:219], 0
	v_mfma_f32_16x16x32_bf16 v[128:131], v[140:143], v[172:175], v[128:131]
	v_mfma_f32_16x16x32_bf16 v[124:127], v[148:151], v[172:175], v[124:127]
	v_mfma_f32_16x16x32_bf16 v[120:123], v[140:143], v[194:197], v[120:123]
	v_mfma_f32_16x16x32_bf16 v[116:119], v[148:151], v[194:197], v[116:119]
	v_mfma_f32_16x16x32_bf16 v[112:115], v[140:143], v[202:205], v[112:115]
	v_mfma_f32_16x16x32_bf16 v[108:111], v[148:151], v[202:205], v[108:111]
	v_mfma_f32_16x16x32_bf16 v[104:107], v[140:143], v[220:223], v[104:107]
	v_mfma_f32_16x16x32_bf16 v[100:103], v[148:151], v[220:223], v[100:103]
	s_setprio 0
	s_setprio 1
	v_mfma_f32_16x16x32_bf16 v[96:99], v[152:155], v[168:171], 0
	v_mfma_f32_16x16x32_bf16 v[92:95], v[160:163], v[168:171], 0
	v_mfma_f32_16x16x32_bf16 v[88:91], v[152:155], v[176:179], 0
	v_mfma_f32_16x16x32_bf16 v[84:87], v[160:163], v[176:179], 0
	v_mfma_f32_16x16x32_bf16 v[80:83], v[152:155], v[198:201], 0
	v_mfma_f32_16x16x32_bf16 v[76:79], v[160:163], v[198:201], 0
	v_mfma_f32_16x16x32_bf16 v[72:75], v[152:155], v[216:219], 0
	v_mfma_f32_16x16x32_bf16 v[68:71], v[160:163], v[216:219], 0
	v_mfma_f32_16x16x32_bf16 v[96:99], v[156:159], v[172:175], v[96:99]
	v_mfma_f32_16x16x32_bf16 v[92:95], v[164:167], v[172:175], v[92:95]
	v_mfma_f32_16x16x32_bf16 v[88:91], v[156:159], v[194:197], v[88:91]
	v_mfma_f32_16x16x32_bf16 v[84:87], v[164:167], v[194:197], v[84:87]
	v_mfma_f32_16x16x32_bf16 v[80:83], v[156:159], v[202:205], v[80:83]
	v_mfma_f32_16x16x32_bf16 v[76:79], v[164:167], v[202:205], v[76:79]
	v_mfma_f32_16x16x32_bf16 v[72:75], v[156:159], v[220:223], v[72:75]
	v_mfma_f32_16x16x32_bf16 v[68:71], v[164:167], v[220:223], v[68:71]
	s_setprio 0
	s_barrier
	s_add_i32 s24, s25, s81
	v_lshl_add_u64 v[224:225], s[10:11], 0, v[182:183]
	s_mov_b32 m0, s24
	ds_read_b128 v[168:171], v213 offset:16384
	ds_read_b128 v[172:175], v213 offset:17408
	ds_read_b128 v[176:179], v213 offset:18432
	ds_read_b128 v[194:197], v213 offset:19456
	ds_read_b128 v[198:201], v213 offset:20480
	ds_read_b128 v[202:205], v213 offset:21504
	ds_read_b128 v[216:219], v213 offset:22528
	ds_read_b128 v[220:223], v213 offset:23552
	global_load_lds_dwordx4 v[224:225], off
	s_add_i32 m0, s24, 0x2000
	s_add_u32 s24, s10, 0x40000
	v_lshl_add_u64 v[232:233], s[10:11], 0, v[186:187]
	s_addc_u32 s25, s11, 0
	s_add_i32 s18, s18, s81
	global_load_lds_dwordx4 v[232:233], off
	v_lshl_add_u64 v[234:235], s[24:25], 0, v[182:183]
	s_mov_b32 m0, s18
	v_lshl_add_u64 v[238:239], s[14:15], 0, v[184:185]
	global_load_lds_dwordx4 v[234:235], off
	v_lshl_add_u64 v[234:235], s[24:25], 0, v[186:187]
	s_add_i32 m0, s18, 0x2000
	s_nop 0
	global_load_lds_dwordx4 v[234:235], off
	v_lshl_add_u64 v[234:235], s[14:15], 0, v[180:181]
	s_mov_b32 m0, s51
	s_nop 0
	global_load_lds_dwordx4 v[234:235], off
	s_mov_b32 m0, s57
	s_nop 0
	global_load_lds_dwordx4 v[238:239], off
	s_cmp_eq_u32 s100, 0
	s_cbranch_scc1 .Lvrp_a2_strict
	s_waitcnt vmcnt(24)
	s_sub_u32 s100, s100, 1
	s_branch .Lvrp_a2_done

.Lvrp_a2_done:
	s_waitcnt lgkmcnt(0)
	s_barrier
	s_setprio 1
	s_waitcnt lgkmcnt(0)
	v_mfma_f32_16x16x32_bf16 v[64:67], v[136:139], v[168:171], 0
	v_mfma_f32_16x16x32_bf16 v[60:63], v[144:147], v[168:171], 0
	v_mfma_f32_16x16x32_bf16 v[56:59], v[136:139], v[176:179], 0
	v_mfma_f32_16x16x32_bf16 v[52:55], v[144:147], v[176:179], 0
	v_mfma_f32_16x16x32_bf16 v[48:51], v[136:139], v[198:201], 0
	v_mfma_f32_16x16x32_bf16 v[44:47], v[144:147], v[198:201], 0
	v_mfma_f32_16x16x32_bf16 v[40:43], v[136:139], v[216:219], 0
	v_mfma_f32_16x16x32_bf16 v[36:39], v[144:147], v[216:219], 0
	v_mfma_f32_16x16x32_bf16 v[64:67], v[140:143], v[172:175], v[64:67]
	v_mfma_f32_16x16x32_bf16 v[60:63], v[148:151], v[172:175], v[60:63]
	v_mfma_f32_16x16x32_bf16 v[56:59], v[140:143], v[194:197], v[56:59]
	v_mfma_f32_16x16x32_bf16 v[52:55], v[148:151], v[194:197], v[52:55]
	v_mfma_f32_16x16x32_bf16 v[48:51], v[140:143], v[202:205], v[48:51]
	v_mfma_f32_16x16x32_bf16 v[44:47], v[148:151], v[202:205], v[44:47]
	v_mfma_f32_16x16x32_bf16 v[40:43], v[140:143], v[220:223], v[40:43]
	v_mfma_f32_16x16x32_bf16 v[36:39], v[148:151], v[220:223], v[36:39]
	s_setprio 0
	s_setprio 1
	v_mfma_f32_16x16x32_bf16 v[32:35], v[152:155], v[168:171], 0
	v_mfma_f32_16x16x32_bf16 v[28:31], v[160:163], v[168:171], 0
	v_mfma_f32_16x16x32_bf16 v[24:27], v[152:155], v[176:179], 0
	v_mfma_f32_16x16x32_bf16 v[20:23], v[160:163], v[176:179], 0
	v_mfma_f32_16x16x32_bf16 v[16:19], v[152:155], v[198:201], 0
	v_mfma_f32_16x16x32_bf16 v[10:13], v[160:163], v[198:201], 0
	v_mfma_f32_16x16x32_bf16 v[6:9], v[152:155], v[216:219], 0
	v_mfma_f32_16x16x32_bf16 v[2:5], v[160:163], v[216:219], 0
	v_mfma_f32_16x16x32_bf16 v[32:35], v[156:159], v[172:175], v[32:35]
	v_mfma_f32_16x16x32_bf16 v[28:31], v[164:167], v[172:175], v[28:31]
	v_mfma_f32_16x16x32_bf16 v[24:27], v[156:159], v[194:197], v[24:27]
	v_mfma_f32_16x16x32_bf16 v[20:23], v[164:167], v[194:197], v[20:23]
	v_mfma_f32_16x16x32_bf16 v[16:19], v[156:159], v[202:205], v[16:19]
	v_mfma_f32_16x16x32_bf16 v[10:13], v[164:167], v[202:205], v[10:13]
	v_mfma_f32_16x16x32_bf16 v[6:9], v[156:159], v[220:223], v[6:9]
	v_mfma_f32_16x16x32_bf16 v[2:5], v[164:167], v[220:223], v[2:5]
	s_setprio 0
	s_barrier
	s_add_i32 s18, 0, 0x18000
	v_add_u32_e32 v14, s18, v206
	s_add_i32 s24, 0, 0x1c000
	ds_read_b128 v[136:139], v14
	ds_read_b128 v[140:143], v14 offset:1024
	ds_read_b128 v[144:147], v14 offset:2048
	ds_read_b128 v[148:151], v14 offset:3072
	v_add_u32_e32 v14, s24, v206
	ds_read_b128 v[152:155], v14
	ds_read_b128 v[156:159], v14 offset:1024
	ds_read_b128 v[160:163], v14 offset:2048
	ds_read_b128 v[164:167], v14 offset:3072
	s_add_u32 s14, s14, 0x40000
	s_addc_u32 s15, s15, 0
	s_mov_b32 m0, s48
	v_lshl_add_u64 v[240:241], s[14:15], 0, v[180:181]
	ds_read_b128 v[168:171], v213 offset:32768
	ds_read_b128 v[172:175], v213 offset:33792
	ds_read_b128 v[176:179], v213 offset:34816
	ds_read_b128 v[194:197], v213 offset:35840
	ds_read_b128 v[198:201], v213 offset:36864
	ds_read_b128 v[202:205], v213 offset:37888
	ds_read_b128 v[216:219], v213 offset:38912
	ds_read_b128 v[220:223], v213 offset:39936
	global_load_lds_dwordx4 v[240:241], off
	v_lshl_add_u64 v[240:241], s[14:15], 0, v[184:185]
	s_mov_b32 m0, s49
	s_nop 0
	global_load_lds_dwordx4 v[240:241], off
	s_waitcnt vmcnt(8)
	s_waitcnt lgkmcnt(0)
	s_barrier
	s_setprio 1
	s_waitcnt lgkmcnt(0)
	v_mfma_f32_16x16x32_bf16 v[128:131], v[136:139], v[168:171], v[128:131]
	v_mfma_f32_16x16x32_bf16 v[124:127], v[144:147], v[168:171], v[124:127]
	v_mfma_f32_16x16x32_bf16 v[120:123], v[136:139], v[176:179], v[120:123]
	v_mfma_f32_16x16x32_bf16 v[116:119], v[144:147], v[176:179], v[116:119]
	v_mfma_f32_16x16x32_bf16 v[112:115], v[136:139], v[198:201], v[112:115]
	v_mfma_f32_16x16x32_bf16 v[108:111], v[144:147], v[198:201], v[108:111]
	v_mfma_f32_16x16x32_bf16 v[104:107], v[136:139], v[216:219], v[104:107]
	v_mfma_f32_16x16x32_bf16 v[100:103], v[144:147], v[216:219], v[100:103]
	v_mfma_f32_16x16x32_bf16 v[128:131], v[140:143], v[172:175], v[128:131]
	v_mfma_f32_16x16x32_bf16 v[124:127], v[148:151], v[172:175], v[124:127]
	v_mfma_f32_16x16x32_bf16 v[120:123], v[140:143], v[194:197], v[120:123]
	v_mfma_f32_16x16x32_bf16 v[116:119], v[148:151], v[194:197], v[116:119]
	v_mfma_f32_16x16x32_bf16 v[112:115], v[140:143], v[202:205], v[112:115]
	v_mfma_f32_16x16x32_bf16 v[108:111], v[148:151], v[202:205], v[108:111]
	v_mfma_f32_16x16x32_bf16 v[104:107], v[140:143], v[220:223], v[104:107]
	v_mfma_f32_16x16x32_bf16 v[100:103], v[148:151], v[220:223], v[100:103]
	s_setprio 0
	s_setprio 1
	v_mfma_f32_16x16x32_bf16 v[96:99], v[152:155], v[168:171], v[96:99]
	v_mfma_f32_16x16x32_bf16 v[92:95], v[160:163], v[168:171], v[92:95]
	v_mfma_f32_16x16x32_bf16 v[88:91], v[152:155], v[176:179], v[88:91]
	v_mfma_f32_16x16x32_bf16 v[84:87], v[160:163], v[176:179], v[84:87]
	v_mfma_f32_16x16x32_bf16 v[80:83], v[152:155], v[198:201], v[80:83]
	v_mfma_f32_16x16x32_bf16 v[76:79], v[160:163], v[198:201], v[76:79]
	v_mfma_f32_16x16x32_bf16 v[72:75], v[152:155], v[216:219], v[72:75]
	v_mfma_f32_16x16x32_bf16 v[68:71], v[160:163], v[216:219], v[68:71]
	v_mfma_f32_16x16x32_bf16 v[96:99], v[156:159], v[172:175], v[96:99]
	v_mfma_f32_16x16x32_bf16 v[92:95], v[164:167], v[172:175], v[92:95]
	v_mfma_f32_16x16x32_bf16 v[88:91], v[156:159], v[194:197], v[88:91]
	v_mfma_f32_16x16x32_bf16 v[84:87], v[164:167], v[194:197], v[84:87]
	v_mfma_f32_16x16x32_bf16 v[80:83], v[156:159], v[202:205], v[80:83]
	v_mfma_f32_16x16x32_bf16 v[76:79], v[164:167], v[202:205], v[76:79]
	v_mfma_f32_16x16x32_bf16 v[72:75], v[156:159], v[220:223], v[72:75]
	v_mfma_f32_16x16x32_bf16 v[68:71], v[164:167], v[220:223], v[68:71]
	s_setprio 0
	s_barrier
	s_add_i32 s14, s18, s81
	v_lshl_add_u64 v[224:225], v[224:225], 0, s[34:35]
	s_mov_b32 m0, s14
	ds_read_b128 v[168:171], v213 offset:49152
	ds_read_b128 v[172:175], v213 offset:50176
	ds_read_b128 v[176:179], v213 offset:51200
	ds_read_b128 v[194:197], v213 offset:52224
	ds_read_b128 v[198:201], v213 offset:53248
	ds_read_b128 v[202:205], v213 offset:54272
	ds_read_b128 v[216:219], v213 offset:55296
	ds_read_b128 v[220:223], v213 offset:56320
	global_load_lds_dwordx4 v[224:225], off
	s_add_i32 m0, s14, 0x2000
	s_add_u32 s10, s10, 0x40080
	v_lshl_add_u64 v[224:225], v[232:233], 0, s[34:35]
	s_addc_u32 s11, s11, 0
	s_add_i32 s14, s24, s81
	global_load_lds_dwordx4 v[224:225], off
	v_lshl_add_u64 v[224:225], s[10:11], 0, v[182:183]
	s_mov_b32 m0, s14
	s_nop 0
	global_load_lds_dwordx4 v[224:225], off
	v_lshl_add_u64 v[224:225], s[10:11], 0, v[186:187]
	s_add_i32 m0, s14, 0x2000
	s_nop 0
	global_load_lds_dwordx4 v[224:225], off
	v_lshl_add_u64 v[224:225], v[234:235], 0, s[34:35]
	s_mov_b32 m0, s47
	s_nop 0
	global_load_lds_dwordx4 v[224:225], off
	v_lshl_add_u64 v[224:225], v[238:239], 0, s[34:35]
	s_mov_b32 m0, s0
	s_nop 0
	global_load_lds_dwordx4 v[224:225], off
	s_waitcnt vmcnt(8)
	s_waitcnt lgkmcnt(0)
	s_barrier
	s_setprio 1
	s_waitcnt lgkmcnt(0)
	v_mfma_f32_16x16x32_bf16 v[64:67], v[136:139], v[168:171], v[64:67]
	v_mfma_f32_16x16x32_bf16 v[60:63], v[144:147], v[168:171], v[60:63]
	v_mfma_f32_16x16x32_bf16 v[56:59], v[136:139], v[176:179], v[56:59]
	v_mfma_f32_16x16x32_bf16 v[52:55], v[144:147], v[176:179], v[52:55]
	v_mfma_f32_16x16x32_bf16 v[48:51], v[136:139], v[198:201], v[48:51]
	v_mfma_f32_16x16x32_bf16 v[44:47], v[144:147], v[198:201], v[44:47]
	v_mfma_f32_16x16x32_bf16 v[40:43], v[136:139], v[216:219], v[40:43]
	v_mfma_f32_16x16x32_bf16 v[36:39], v[144:147], v[216:219], v[36:39]
	v_mfma_f32_16x16x32_bf16 v[64:67], v[140:143], v[172:175], v[64:67]
	v_mfma_f32_16x16x32_bf16 v[60:63], v[148:151], v[172:175], v[60:63]
	v_mfma_f32_16x16x32_bf16 v[56:59], v[140:143], v[194:197], v[56:59]
	v_mfma_f32_16x16x32_bf16 v[52:55], v[148:151], v[194:197], v[52:55]
	v_mfma_f32_16x16x32_bf16 v[48:51], v[140:143], v[202:205], v[48:51]
	v_mfma_f32_16x16x32_bf16 v[44:47], v[148:151], v[202:205], v[44:47]
	v_mfma_f32_16x16x32_bf16 v[40:43], v[140:143], v[220:223], v[40:43]
	v_mfma_f32_16x16x32_bf16 v[36:39], v[148:151], v[220:223], v[36:39]
	s_setprio 0
	s_setprio 1
	v_mfma_f32_16x16x32_bf16 v[32:35], v[152:155], v[168:171], v[32:35]
	v_mfma_f32_16x16x32_bf16 v[28:31], v[160:163], v[168:171], v[28:31]
	v_mfma_f32_16x16x32_bf16 v[24:27], v[152:155], v[176:179], v[24:27]
	v_mfma_f32_16x16x32_bf16 v[20:23], v[160:163], v[176:179], v[20:23]
	v_mfma_f32_16x16x32_bf16 v[16:19], v[152:155], v[198:201], v[16:19]
	v_mfma_f32_16x16x32_bf16 v[10:13], v[160:163], v[198:201], v[10:13]
	v_mfma_f32_16x16x32_bf16 v[6:9], v[152:155], v[216:219], v[6:9]
	v_mfma_f32_16x16x32_bf16 v[2:5], v[160:163], v[216:219], v[2:5]
	v_mfma_f32_16x16x32_bf16 v[32:35], v[156:159], v[172:175], v[32:35]
	v_mfma_f32_16x16x32_bf16 v[28:31], v[164:167], v[172:175], v[28:31]
	v_mfma_f32_16x16x32_bf16 v[24:27], v[156:159], v[194:197], v[24:27]
	v_mfma_f32_16x16x32_bf16 v[20:23], v[164:167], v[194:197], v[20:23]
	v_mfma_f32_16x16x32_bf16 v[16:19], v[156:159], v[202:205], v[16:19]
	v_mfma_f32_16x16x32_bf16 v[10:13], v[164:167], v[202:205], v[10:13]
	v_mfma_f32_16x16x32_bf16 v[6:9], v[156:159], v[220:223], v[6:9]
	v_mfma_f32_16x16x32_bf16 v[2:5], v[164:167], v[220:223], v[2:5]
	s_setprio 0
	s_barrier
	s_add_i32 s17, s17, 2
	s_add_u32 s8, s8, 0x100
	s_addc_u32 s9, s9, 0
	s_cmp_gt_u32 s17, 13
	s_cbranch_scc1 .Lkexit_a
	.p2align	6
.LBB0_413:
	s_add_u32 s10, s54, s8
	s_addc_u32 s11, s55, s9
	s_add_u32 s10, s10, 0x100
	s_addc_u32 s11, s11, 0
	s_add_u32 s18, s78, s8
	s_addc_u32 s24, s1, s9
	s_add_i32 s25, 0, 0x10000
	s_cmpk_eq_i32 s8, 0x700
	s_cselect_b32 s15, s4, s11
	s_cselect_b32 s14, s5, s10
	v_add_u32_e32 v14, s25, v206
	s_cselect_b32 s11, s12, s24
	s_cselect_b32 s10, s13, s18
	s_add_i32 s18, 0, 0x14000
	ds_read_b128 v[136:139], v14
	ds_read_b128 v[140:143], v14 offset:1024
	ds_read_b128 v[144:147], v14 offset:2048
	ds_read_b128 v[148:151], v14 offset:3072
	v_add_u32_e32 v14, s18, v206
	ds_read_b128 v[152:155], v14
	ds_read_b128 v[156:159], v14 offset:1024
	ds_read_b128 v[160:163], v14 offset:2048
	ds_read_b128 v[164:167], v14 offset:3072
	v_lshl_add_u64 v[224:225], v[132:133], 0, s[8:9]
	s_add_i32 m0, s51, 0xc000
	ds_read_b128 v[168:171], v213
	ds_read_b128 v[172:175], v213 offset:1024
	ds_read_b128 v[176:179], v213 offset:2048
	ds_read_b128 v[194:197], v213 offset:3072
	ds_read_b128 v[198:201], v213 offset:4096
	ds_read_b128 v[202:205], v213 offset:5120
	ds_read_b128 v[216:219], v213 offset:6144
	ds_read_b128 v[220:223], v213 offset:7168
	global_load_lds_dwordx4 v[224:225], off
	v_lshl_add_u64 v[224:225], v[134:135], 0, s[8:9]
	s_add_i32 m0, s51, 0xe000
	s_nop 0
	global_load_lds_dwordx4 v[224:225], off
	s_waitcnt vmcnt(8)
	s_waitcnt lgkmcnt(0)
	s_barrier
	s_setprio 1
	s_waitcnt lgkmcnt(0)
	v_mfma_f32_16x16x32_bf16 v[128:131], v[136:139], v[168:171], v[128:131]
	v_mfma_f32_16x16x32_bf16 v[124:127], v[144:147], v[168:171], v[124:127]
	v_mfma_f32_16x16x32_bf16 v[120:123], v[136:139], v[176:179], v[120:123]
	v_mfma_f32_16x16x32_bf16 v[116:119], v[144:147], v[176:179], v[116:119]
	v_mfma_f32_16x16x32_bf16 v[112:115], v[136:139], v[198:201], v[112:115]
	v_mfma_f32_16x16x32_bf16 v[108:111], v[144:147], v[198:201], v[108:111]
	v_mfma_f32_16x16x32_bf16 v[104:107], v[136:139], v[216:219], v[104:107]
	v_mfma_f32_16x16x32_bf16 v[100:103], v[144:147], v[216:219], v[100:103]
	v_mfma_f32_16x16x32_bf16 v[128:131], v[140:143], v[172:175], v[128:131]
	v_mfma_f32_16x16x32_bf16 v[124:127], v[148:151], v[172:175], v[124:127]
	v_mfma_f32_16x16x32_bf16 v[120:123], v[140:143], v[194:197], v[120:123]
	v_mfma_f32_16x16x32_bf16 v[116:119], v[148:151], v[194:197], v[116:119]
	v_mfma_f32_16x16x32_bf16 v[112:115], v[140:143], v[202:205], v[112:115]
	v_mfma_f32_16x16x32_bf16 v[108:111], v[148:151], v[202:205], v[108:111]
	v_mfma_f32_16x16x32_bf16 v[104:107], v[140:143], v[220:223], v[104:107]
	v_mfma_f32_16x16x32_bf16 v[100:103], v[148:151], v[220:223], v[100:103]
	s_setprio 0
	s_setprio 1
	v_mfma_f32_16x16x32_bf16 v[96:99], v[152:155], v[168:171], v[96:99]
	v_mfma_f32_16x16x32_bf16 v[92:95], v[160:163], v[168:171], v[92:95]
	v_mfma_f32_16x16x32_bf16 v[88:91], v[152:155], v[176:179], v[88:91]
	v_mfma_f32_16x16x32_bf16 v[84:87], v[160:163], v[176:179], v[84:87]
	v_mfma_f32_16x16x32_bf16 v[80:83], v[152:155], v[198:201], v[80:83]
	v_mfma_f32_16x16x32_bf16 v[76:79], v[160:163], v[198:201], v[76:79]
	v_mfma_f32_16x16x32_bf16 v[72:75], v[152:155], v[216:219], v[72:75]
	v_mfma_f32_16x16x32_bf16 v[68:71], v[160:163], v[216:219], v[68:71]
	v_mfma_f32_16x16x32_bf16 v[96:99], v[156:159], v[172:175], v[96:99]
	v_mfma_f32_16x16x32_bf16 v[92:95], v[164:167], v[172:175], v[92:95]
	v_mfma_f32_16x16x32_bf16 v[88:91], v[156:159], v[194:197], v[88:91]
	v_mfma_f32_16x16x32_bf16 v[84:87], v[164:167], v[194:197], v[84:87]
	v_mfma_f32_16x16x32_bf16 v[80:83], v[156:159], v[202:205], v[80:83]
	v_mfma_f32_16x16x32_bf16 v[76:79], v[164:167], v[202:205], v[76:79]
	v_mfma_f32_16x16x32_bf16 v[72:75], v[156:159], v[220:223], v[72:75]
	v_mfma_f32_16x16x32_bf16 v[68:71], v[164:167], v[220:223], v[68:71]
	s_setprio 0
	s_barrier
	s_add_i32 s24, s25, s81
	v_lshl_add_u64 v[224:225], s[10:11], 0, v[182:183]
	s_mov_b32 m0, s24
	ds_read_b128 v[168:171], v213 offset:16384
	ds_read_b128 v[172:175], v213 offset:17408
	ds_read_b128 v[176:179], v213 offset:18432
	ds_read_b128 v[194:197], v213 offset:19456
	ds_read_b128 v[198:201], v213 offset:20480
	ds_read_b128 v[202:205], v213 offset:21504
	ds_read_b128 v[216:219], v213 offset:22528
	ds_read_b128 v[220:223], v213 offset:23552
	global_load_lds_dwordx4 v[224:225], off
	s_add_i32 m0, s24, 0x2000
	s_add_u32 s24, s10, 0x40000
	v_lshl_add_u64 v[232:233], s[10:11], 0, v[186:187]
	s_addc_u32 s25, s11, 0
	s_add_i32 s18, s18, s81
	global_load_lds_dwordx4 v[232:233], off
	v_lshl_add_u64 v[234:235], s[24:25], 0, v[182:183]
	s_mov_b32 m0, s18
	v_lshl_add_u64 v[238:239], s[14:15], 0, v[184:185]
	global_load_lds_dwordx4 v[234:235], off
	v_lshl_add_u64 v[234:235], s[24:25], 0, v[186:187]
	s_add_i32 m0, s18, 0x2000
	s_nop 0
	global_load_lds_dwordx4 v[234:235], off
	v_lshl_add_u64 v[234:235], s[14:15], 0, v[180:181]
	s_mov_b32 m0, s51
	s_nop 0
	global_load_lds_dwordx4 v[234:235], off
	s_mov_b32 m0, s57
	s_nop 0
	global_load_lds_dwordx4 v[238:239], off
	s_waitcnt vmcnt(8)
	s_waitcnt lgkmcnt(0)
	s_barrier
	s_setprio 1
	s_waitcnt lgkmcnt(0)
	v_mfma_f32_16x16x32_bf16 v[64:67], v[136:139], v[168:171], v[64:67]
	v_mfma_f32_16x16x32_bf16 v[60:63], v[144:147], v[168:171], v[60:63]
	v_mfma_f32_16x16x32_bf16 v[56:59], v[136:139], v[176:179], v[56:59]
	v_mfma_f32_16x16x32_bf16 v[52:55], v[144:147], v[176:179], v[52:55]
	v_mfma_f32_16x16x32_bf16 v[48:51], v[136:139], v[198:201], v[48:51]
	v_mfma_f32_16x16x32_bf16 v[44:47], v[144:147], v[198:201], v[44:47]
	v_mfma_f32_16x16x32_bf16 v[40:43], v[136:139], v[216:219], v[40:43]
	v_mfma_f32_16x16x32_bf16 v[36:39], v[144:147], v[216:219], v[36:39]
	v_mfma_f32_16x16x32_bf16 v[64:67], v[140:143], v[172:175], v[64:67]
	v_mfma_f32_16x16x32_bf16 v[60:63], v[148:151], v[172:175], v[60:63]
	v_mfma_f32_16x16x32_bf16 v[56:59], v[140:143], v[194:197], v[56:59]
	v_mfma_f32_16x16x32_bf16 v[52:55], v[148:151], v[194:197], v[52:55]
	v_mfma_f32_16x16x32_bf16 v[48:51], v[140:143], v[202:205], v[48:51]
	v_mfma_f32_16x16x32_bf16 v[44:47], v[148:151], v[202:205], v[44:47]
	v_mfma_f32_16x16x32_bf16 v[40:43], v[140:143], v[220:223], v[40:43]
	v_mfma_f32_16x16x32_bf16 v[36:39], v[148:151], v[220:223], v[36:39]
	s_setprio 0
	s_setprio 1
	v_mfma_f32_16x16x32_bf16 v[32:35], v[152:155], v[168:171], v[32:35]
	v_mfma_f32_16x16x32_bf16 v[28:31], v[160:163], v[168:171], v[28:31]
	v_mfma_f32_16x16x32_bf16 v[24:27], v[152:155], v[176:179], v[24:27]
	v_mfma_f32_16x16x32_bf16 v[20:23], v[160:163], v[176:179], v[20:23]
	v_mfma_f32_16x16x32_bf16 v[16:19], v[152:155], v[198:201], v[16:19]
	v_mfma_f32_16x16x32_bf16 v[10:13], v[160:163], v[198:201], v[10:13]
	v_mfma_f32_16x16x32_bf16 v[6:9], v[152:155], v[216:219], v[6:9]
	v_mfma_f32_16x16x32_bf16 v[2:5], v[160:163], v[216:219], v[2:5]
	v_mfma_f32_16x16x32_bf16 v[32:35], v[156:159], v[172:175], v[32:35]
	v_mfma_f32_16x16x32_bf16 v[28:31], v[164:167], v[172:175], v[28:31]
	v_mfma_f32_16x16x32_bf16 v[24:27], v[156:159], v[194:197], v[24:27]
	v_mfma_f32_16x16x32_bf16 v[20:23], v[164:167], v[194:197], v[20:23]
	v_mfma_f32_16x16x32_bf16 v[16:19], v[156:159], v[202:205], v[16:19]
	v_mfma_f32_16x16x32_bf16 v[10:13], v[164:167], v[202:205], v[10:13]
	v_mfma_f32_16x16x32_bf16 v[6:9], v[156:159], v[220:223], v[6:9]
	v_mfma_f32_16x16x32_bf16 v[2:5], v[164:167], v[220:223], v[2:5]
	s_setprio 0
	s_barrier
	s_add_i32 s18, 0, 0x18000
	v_add_u32_e32 v14, s18, v206
	s_add_i32 s24, 0, 0x1c000
	ds_read_b128 v[136:139], v14
	ds_read_b128 v[140:143], v14 offset:1024
	ds_read_b128 v[144:147], v14 offset:2048
	ds_read_b128 v[148:151], v14 offset:3072
	v_add_u32_e32 v14, s24, v206
	ds_read_b128 v[152:155], v14
	ds_read_b128 v[156:159], v14 offset:1024
	ds_read_b128 v[160:163], v14 offset:2048
	ds_read_b128 v[164:167], v14 offset:3072
	s_add_u32 s14, s14, 0x40000
	s_addc_u32 s15, s15, 0
	s_mov_b32 m0, s48
	v_lshl_add_u64 v[240:241], s[14:15], 0, v[180:181]
	ds_read_b128 v[168:171], v213 offset:32768
	ds_read_b128 v[172:175], v213 offset:33792
	ds_read_b128 v[176:179], v213 offset:34816
	ds_read_b128 v[194:197], v213 offset:35840
	ds_read_b128 v[198:201], v213 offset:36864
	ds_read_b128 v[202:205], v213 offset:37888
	ds_read_b128 v[216:219], v213 offset:38912
	ds_read_b128 v[220:223], v213 offset:39936
	global_load_lds_dwordx4 v[240:241], off
	v_lshl_add_u64 v[240:241], s[14:15], 0, v[184:185]
	s_mov_b32 m0, s49
	s_nop 0
	global_load_lds_dwordx4 v[240:241], off
	s_waitcnt vmcnt(8)
	s_waitcnt lgkmcnt(0)
	s_barrier
	s_setprio 1
	s_waitcnt lgkmcnt(0)
	v_mfma_f32_16x16x32_bf16 v[128:131], v[136:139], v[168:171], v[128:131]
	v_mfma_f32_16x16x32_bf16 v[124:127], v[144:147], v[168:171], v[124:127]
	v_mfma_f32_16x16x32_bf16 v[120:123], v[136:139], v[176:179], v[120:123]
	v_mfma_f32_16x16x32_bf16 v[116:119], v[144:147], v[176:179], v[116:119]
	v_mfma_f32_16x16x32_bf16 v[112:115], v[136:139], v[198:201], v[112:115]
	v_mfma_f32_16x16x32_bf16 v[108:111], v[144:147], v[198:201], v[108:111]
	v_mfma_f32_16x16x32_bf16 v[104:107], v[136:139], v[216:219], v[104:107]
	v_mfma_f32_16x16x32_bf16 v[100:103], v[144:147], v[216:219], v[100:103]
	v_mfma_f32_16x16x32_bf16 v[128:131], v[140:143], v[172:175], v[128:131]
	v_mfma_f32_16x16x32_bf16 v[124:127], v[148:151], v[172:175], v[124:127]
	v_mfma_f32_16x16x32_bf16 v[120:123], v[140:143], v[194:197], v[120:123]
	v_mfma_f32_16x16x32_bf16 v[116:119], v[148:151], v[194:197], v[116:119]
	v_mfma_f32_16x16x32_bf16 v[112:115], v[140:143], v[202:205], v[112:115]
	v_mfma_f32_16x16x32_bf16 v[108:111], v[148:151], v[202:205], v[108:111]
	v_mfma_f32_16x16x32_bf16 v[104:107], v[140:143], v[220:223], v[104:107]
	v_mfma_f32_16x16x32_bf16 v[100:103], v[148:151], v[220:223], v[100:103]
	s_setprio 0
	s_setprio 1
	v_mfma_f32_16x16x32_bf16 v[96:99], v[152:155], v[168:171], v[96:99]
	v_mfma_f32_16x16x32_bf16 v[92:95], v[160:163], v[168:171], v[92:95]
	v_mfma_f32_16x16x32_bf16 v[88:91], v[152:155], v[176:179], v[88:91]
	v_mfma_f32_16x16x32_bf16 v[84:87], v[160:163], v[176:179], v[84:87]
	v_mfma_f32_16x16x32_bf16 v[80:83], v[152:155], v[198:201], v[80:83]
	v_mfma_f32_16x16x32_bf16 v[76:79], v[160:163], v[198:201], v[76:79]
	v_mfma_f32_16x16x32_bf16 v[72:75], v[152:155], v[216:219], v[72:75]
	v_mfma_f32_16x16x32_bf16 v[68:71], v[160:163], v[216:219], v[68:71]
	v_mfma_f32_16x16x32_bf16 v[96:99], v[156:159], v[172:175], v[96:99]
	v_mfma_f32_16x16x32_bf16 v[92:95], v[164:167], v[172:175], v[92:95]
	v_mfma_f32_16x16x32_bf16 v[88:91], v[156:159], v[194:197], v[88:91]
	v_mfma_f32_16x16x32_bf16 v[84:87], v[164:167], v[194:197], v[84:87]
	v_mfma_f32_16x16x32_bf16 v[80:83], v[156:159], v[202:205], v[80:83]
	v_mfma_f32_16x16x32_bf16 v[76:79], v[164:167], v[202:205], v[76:79]
	v_mfma_f32_16x16x32_bf16 v[72:75], v[156:159], v[220:223], v[72:75]
	v_mfma_f32_16x16x32_bf16 v[68:71], v[164:167], v[220:223], v[68:71]
	s_setprio 0
	s_barrier
	s_add_i32 s14, s18, s81
	v_lshl_add_u64 v[224:225], v[224:225], 0, s[34:35]
	s_mov_b32 m0, s14
	ds_read_b128 v[168:171], v213 offset:49152
	ds_read_b128 v[172:175], v213 offset:50176
	ds_read_b128 v[176:179], v213 offset:51200
	ds_read_b128 v[194:197], v213 offset:52224
	ds_read_b128 v[198:201], v213 offset:53248
	ds_read_b128 v[202:205], v213 offset:54272
	ds_read_b128 v[216:219], v213 offset:55296
	ds_read_b128 v[220:223], v213 offset:56320
	global_load_lds_dwordx4 v[224:225], off
	s_add_i32 m0, s14, 0x2000
	s_add_u32 s10, s10, 0x40080
	v_lshl_add_u64 v[224:225], v[232:233], 0, s[34:35]
	s_addc_u32 s11, s11, 0
	s_add_i32 s14, s24, s81
	global_load_lds_dwordx4 v[224:225], off
	v_lshl_add_u64 v[224:225], s[10:11], 0, v[182:183]
	s_mov_b32 m0, s14
	s_nop 0
	global_load_lds_dwordx4 v[224:225], off
	v_lshl_add_u64 v[224:225], s[10:11], 0, v[186:187]
	s_add_i32 m0, s14, 0x2000
	s_nop 0
	global_load_lds_dwordx4 v[224:225], off
	v_lshl_add_u64 v[224:225], v[234:235], 0, s[34:35]
	s_mov_b32 m0, s47
	s_nop 0
	global_load_lds_dwordx4 v[224:225], off
	v_lshl_add_u64 v[224:225], v[238:239], 0, s[34:35]
	s_mov_b32 m0, s0
	s_nop 0
	global_load_lds_dwordx4 v[224:225], off
	s_waitcnt vmcnt(8)
	s_waitcnt lgkmcnt(0)
	s_barrier
	s_setprio 1
	s_waitcnt lgkmcnt(0)
	v_mfma_f32_16x16x32_bf16 v[64:67], v[136:139], v[168:171], v[64:67]
	v_mfma_f32_16x16x32_bf16 v[60:63], v[144:147], v[168:171], v[60:63]
	v_mfma_f32_16x16x32_bf16 v[56:59], v[136:139], v[176:179], v[56:59]
	v_mfma_f32_16x16x32_bf16 v[52:55], v[144:147], v[176:179], v[52:55]
	v_mfma_f32_16x16x32_bf16 v[48:51], v[136:139], v[198:201], v[48:51]
	v_mfma_f32_16x16x32_bf16 v[44:47], v[144:147], v[198:201], v[44:47]
	v_mfma_f32_16x16x32_bf16 v[40:43], v[136:139], v[216:219], v[40:43]
	v_mfma_f32_16x16x32_bf16 v[36:39], v[144:147], v[216:219], v[36:39]
	v_mfma_f32_16x16x32_bf16 v[64:67], v[140:143], v[172:175], v[64:67]
	v_mfma_f32_16x16x32_bf16 v[60:63], v[148:151], v[172:175], v[60:63]
	v_mfma_f32_16x16x32_bf16 v[56:59], v[140:143], v[194:197], v[56:59]
	v_mfma_f32_16x16x32_bf16 v[52:55], v[148:151], v[194:197], v[52:55]
	v_mfma_f32_16x16x32_bf16 v[48:51], v[140:143], v[202:205], v[48:51]
	v_mfma_f32_16x16x32_bf16 v[44:47], v[148:151], v[202:205], v[44:47]
	v_mfma_f32_16x16x32_bf16 v[40:43], v[140:143], v[220:223], v[40:43]
	v_mfma_f32_16x16x32_bf16 v[36:39], v[148:151], v[220:223], v[36:39]
	s_setprio 0
	s_setprio 1
	v_mfma_f32_16x16x32_bf16 v[32:35], v[152:155], v[168:171], v[32:35]
	v_mfma_f32_16x16x32_bf16 v[28:31], v[160:163], v[168:171], v[28:31]
	v_mfma_f32_16x16x32_bf16 v[24:27], v[152:155], v[176:179], v[24:27]
	v_mfma_f32_16x16x32_bf16 v[20:23], v[160:163], v[176:179], v[20:23]
	v_mfma_f32_16x16x32_bf16 v[16:19], v[152:155], v[198:201], v[16:19]
	v_mfma_f32_16x16x32_bf16 v[10:13], v[160:163], v[198:201], v[10:13]
	v_mfma_f32_16x16x32_bf16 v[6:9], v[152:155], v[216:219], v[6:9]
	v_mfma_f32_16x16x32_bf16 v[2:5], v[160:163], v[216:219], v[2:5]
	v_mfma_f32_16x16x32_bf16 v[32:35], v[156:159], v[172:175], v[32:35]
	v_mfma_f32_16x16x32_bf16 v[28:31], v[164:167], v[172:175], v[28:31]
	v_mfma_f32_16x16x32_bf16 v[24:27], v[156:159], v[194:197], v[24:27]
	v_mfma_f32_16x16x32_bf16 v[20:23], v[164:167], v[194:197], v[20:23]
	v_mfma_f32_16x16x32_bf16 v[16:19], v[156:159], v[202:205], v[16:19]
	v_mfma_f32_16x16x32_bf16 v[10:13], v[164:167], v[202:205], v[10:13]
	v_mfma_f32_16x16x32_bf16 v[6:9], v[156:159], v[220:223], v[6:9]
	v_mfma_f32_16x16x32_bf16 v[2:5], v[164:167], v[220:223], v[2:5]
	s_setprio 0
	s_barrier
	s_add_i32 s17, s17, 2
	s_add_u32 s8, s8, 0x100
	s_addc_u32 s9, s9, 0
	s_cmp_gt_u32 s17, 13
	s_cbranch_scc0 .LBB0_413
.Lkexit_a:
	s_and_b64 vcc, exec, s[62:63]
	s_cbranch_vccz .LBB0_416
	s_barrier

.LBB0_1754:
	v_readlane_b32 s0, v255, 23
	s_mov_b32 s44, s8
	s_mov_b32 s46, s82
	s_mov_b64 s[20:21], s[2:3]
	s_mov_b64 s[48:49], s[58:59]
	v_writelane_b32 v251, s1, 17

.Lvrp_e1_done:
	s_waitcnt lgkmcnt(0)
	s_barrier
	s_setprio 1
	s_waitcnt lgkmcnt(7)
	v_mfma_f32_16x16x32_bf16 v[130:133], v[134:137], v[166:169], 0
	v_mfma_f32_16x16x32_bf16 v[126:129], v[142:145], v[166:169], 0
	s_waitcnt lgkmcnt(5)
	v_mfma_f32_16x16x32_bf16 v[122:125], v[134:137], v[174:177], 0
	v_mfma_f32_16x16x32_bf16 v[118:121], v[142:145], v[174:177], 0
	s_waitcnt lgkmcnt(3)
	v_mfma_f32_16x16x32_bf16 v[114:117], v[134:137], v[182:185], 0
	v_mfma_f32_16x16x32_bf16 v[110:113], v[142:145], v[182:185], 0
	s_waitcnt lgkmcnt(1)
	v_mfma_f32_16x16x32_bf16 v[106:109], v[134:137], v[190:193], 0
	v_mfma_f32_16x16x32_bf16 v[102:105], v[142:145], v[190:193], 0
	v_mfma_f32_16x16x32_bf16 v[130:133], v[138:141], v[170:173], v[130:133]
	v_mfma_f32_16x16x32_bf16 v[126:129], v[146:149], v[170:173], v[126:129]
	v_mfma_f32_16x16x32_bf16 v[122:125], v[138:141], v[178:181], v[122:125]
	v_mfma_f32_16x16x32_bf16 v[118:121], v[146:149], v[178:181], v[118:121]
	v_mfma_f32_16x16x32_bf16 v[114:117], v[138:141], v[186:189], v[114:117]
	v_mfma_f32_16x16x32_bf16 v[110:113], v[146:149], v[186:189], v[110:113]
	s_waitcnt lgkmcnt(0)
	v_mfma_f32_16x16x32_bf16 v[106:109], v[138:141], v[194:197], v[106:109]
	v_mfma_f32_16x16x32_bf16 v[102:105], v[146:149], v[194:197], v[102:105]
	s_setprio 0
	s_setprio 1
	v_mfma_f32_16x16x32_bf16 v[98:101], v[150:153], v[166:169], 0
	v_mfma_f32_16x16x32_bf16 v[94:97], v[158:161], v[166:169], 0
	v_mfma_f32_16x16x32_bf16 v[90:93], v[150:153], v[174:177], 0
	v_mfma_f32_16x16x32_bf16 v[86:89], v[158:161], v[174:177], 0
	v_mfma_f32_16x16x32_bf16 v[82:85], v[150:153], v[182:185], 0
	v_mfma_f32_16x16x32_bf16 v[78:81], v[158:161], v[182:185], 0
	v_mfma_f32_16x16x32_bf16 v[74:77], v[150:153], v[190:193], 0
	v_mfma_f32_16x16x32_bf16 v[70:73], v[158:161], v[190:193], 0
	v_mfma_f32_16x16x32_bf16 v[98:101], v[154:157], v[170:173], v[98:101]
	v_mfma_f32_16x16x32_bf16 v[94:97], v[162:165], v[170:173], v[94:97]
	v_mfma_f32_16x16x32_bf16 v[90:93], v[154:157], v[178:181], v[90:93]
	v_mfma_f32_16x16x32_bf16 v[86:89], v[162:165], v[178:181], v[86:89]
	v_mfma_f32_16x16x32_bf16 v[82:85], v[154:157], v[186:189], v[82:85]
	v_mfma_f32_16x16x32_bf16 v[78:81], v[162:165], v[186:189], v[78:81]
	v_mfma_f32_16x16x32_bf16 v[74:77], v[154:157], v[194:197], v[74:77]
	v_mfma_f32_16x16x32_bf16 v[70:73], v[162:165], v[194:197], v[70:73]
	s_setprio 0
	s_barrier
	ds_read_b128 v[166:169], v234 offset:16384
	ds_read_b128 v[170:173], v234 offset:17408
	ds_read_b128 v[174:177], v234 offset:18432
	ds_read_b128 v[178:181], v234 offset:19456
	ds_read_b128 v[182:185], v234 offset:20480
	ds_read_b128 v[186:189], v234 offset:21504
	ds_read_b128 v[190:193], v234 offset:22528
	ds_read_b128 v[194:197], v234 offset:23552
	s_mov_b32 m0, s47
	s_nop 0
	global_load_lds_dwordx4 v238, s[14:15]
	s_add_u32 s28, s14, 0x40000
	s_mov_b32 m0, s79
	s_nop 0
	global_load_lds_dwordx4 v240, s[14:15]
	s_addc_u32 s29, s15, 0
	s_mov_b32 m0, s78
	s_nop 0
	global_load_lds_dwordx4 v238, s[28:29]
	s_nop 0
	s_mov_b32 m0, s56
	s_nop 0
	global_load_lds_dwordx4 v240, s[28:29]
	s_nop 0
	s_mov_b32 m0, s45
	s_nop 0
	global_load_lds_dwordx4 v1, s[40:41]
	s_nop 0
	s_mov_b32 m0, s57
	s_nop 0
	global_load_lds_dwordx4 v239, s[40:41]
	s_cmp_eq_u32 s100, 0
	s_cbranch_scc1 .Lvrp_e2_strict
	s_waitcnt vmcnt(16)
	s_sub_u32 s100, s100, 1
	s_branch .Lvrp_e2_done

.Lvrp_e2_done:
	s_waitcnt lgkmcnt(0)
	s_barrier
	s_setprio 1
	s_waitcnt lgkmcnt(7)
	v_mfma_f32_16x16x32_bf16 v[66:69], v[134:137], v[166:169], 0
	v_mfma_f32_16x16x32_bf16 v[62:65], v[142:145], v[166:169], 0
	s_waitcnt lgkmcnt(5)
	v_mfma_f32_16x16x32_bf16 v[58:61], v[134:137], v[174:177], 0
	v_mfma_f32_16x16x32_bf16 v[54:57], v[142:145], v[174:177], 0
	s_waitcnt lgkmcnt(3)
	v_mfma_f32_16x16x32_bf16 v[50:53], v[134:137], v[182:185], 0
	v_mfma_f32_16x16x32_bf16 v[46:49], v[142:145], v[182:185], 0
	s_waitcnt lgkmcnt(1)
	v_mfma_f32_16x16x32_bf16 v[42:45], v[134:137], v[190:193], 0
	v_mfma_f32_16x16x32_bf16 v[38:41], v[142:145], v[190:193], 0
	v_mfma_f32_16x16x32_bf16 v[66:69], v[138:141], v[170:173], v[66:69]
	v_mfma_f32_16x16x32_bf16 v[62:65], v[146:149], v[170:173], v[62:65]
	v_mfma_f32_16x16x32_bf16 v[58:61], v[138:141], v[178:181], v[58:61]
	v_mfma_f32_16x16x32_bf16 v[54:57], v[146:149], v[178:181], v[54:57]
	v_mfma_f32_16x16x32_bf16 v[50:53], v[138:141], v[186:189], v[50:53]
	v_mfma_f32_16x16x32_bf16 v[46:49], v[146:149], v[186:189], v[46:49]
	s_waitcnt lgkmcnt(0)
	v_mfma_f32_16x16x32_bf16 v[42:45], v[138:141], v[194:197], v[42:45]
	v_mfma_f32_16x16x32_bf16 v[38:41], v[146:149], v[194:197], v[38:41]
	s_setprio 0
	s_setprio 1
	v_mfma_f32_16x16x32_bf16 v[34:37], v[150:153], v[166:169], 0
	v_mfma_f32_16x16x32_bf16 v[30:33], v[158:161], v[166:169], 0
	v_mfma_f32_16x16x32_bf16 v[26:29], v[150:153], v[174:177], 0
	v_mfma_f32_16x16x32_bf16 v[22:25], v[158:161], v[174:177], 0
	v_mfma_f32_16x16x32_bf16 v[16:19], v[150:153], v[182:185], 0
	v_mfma_f32_16x16x32_bf16 v[10:13], v[158:161], v[182:185], 0
	v_mfma_f32_16x16x32_bf16 v[6:9], v[150:153], v[190:193], 0
	v_mfma_f32_16x16x32_bf16 v[2:5], v[158:161], v[190:193], 0
	v_mfma_f32_16x16x32_bf16 v[34:37], v[154:157], v[170:173], v[34:37]
	v_mfma_f32_16x16x32_bf16 v[30:33], v[162:165], v[170:173], v[30:33]
	v_mfma_f32_16x16x32_bf16 v[26:29], v[154:157], v[178:181], v[26:29]
	v_mfma_f32_16x16x32_bf16 v[22:25], v[162:165], v[178:181], v[22:25]
	v_mfma_f32_16x16x32_bf16 v[16:19], v[154:157], v[186:189], v[16:19]
	v_mfma_f32_16x16x32_bf16 v[10:13], v[162:165], v[186:189], v[10:13]
	v_mfma_f32_16x16x32_bf16 v[6:9], v[154:157], v[194:197], v[6:9]
	v_mfma_f32_16x16x32_bf16 v[2:5], v[162:165], v[194:197], v[2:5]
	s_setprio 0
	s_barrier
	v_add_u32_e32 v14, 0x18000, v249
	ds_read_b128 v[134:137], v14
	ds_read_b128 v[138:141], v14 offset:1024
	ds_read_b128 v[142:145], v14 offset:2048
	ds_read_b128 v[146:149], v14 offset:3072
	v_add_u32_e32 v14, 0x1c000, v249
	ds_read_b128 v[150:153], v14
	ds_read_b128 v[154:157], v14 offset:1024
	ds_read_b128 v[158:161], v14 offset:2048
	ds_read_b128 v[162:165], v14 offset:3072
	ds_read_b128 v[166:169], v234 offset:32768
	ds_read_b128 v[170:173], v234 offset:33792
	ds_read_b128 v[174:177], v234 offset:34816
	ds_read_b128 v[178:181], v234 offset:35840
	ds_read_b128 v[182:185], v234 offset:36864
	ds_read_b128 v[186:189], v234 offset:37888
	ds_read_b128 v[190:193], v234 offset:38912
	ds_read_b128 v[194:197], v234 offset:39936
	s_add_u32 s28, s40, 0x40000
	s_addc_u32 s29, s41, 0
	s_mov_b32 m0, s76
	s_nop 0
	global_load_lds_dwordx4 v1, s[28:29]
	s_nop 0
	s_mov_b32 m0, s77
	s_nop 0
	global_load_lds_dwordx4 v239, s[28:29]
	s_waitcnt vmcnt(8)
	s_waitcnt lgkmcnt(0)
	s_barrier
	s_setprio 1
	s_waitcnt lgkmcnt(7)
	v_mfma_f32_16x16x32_bf16 v[130:133], v[134:137], v[166:169], v[130:133]
	v_mfma_f32_16x16x32_bf16 v[126:129], v[142:145], v[166:169], v[126:129]
	s_waitcnt lgkmcnt(5)
	v_mfma_f32_16x16x32_bf16 v[122:125], v[134:137], v[174:177], v[122:125]
	v_mfma_f32_16x16x32_bf16 v[118:121], v[142:145], v[174:177], v[118:121]
	s_waitcnt lgkmcnt(3)
	v_mfma_f32_16x16x32_bf16 v[114:117], v[134:137], v[182:185], v[114:117]
	v_mfma_f32_16x16x32_bf16 v[110:113], v[142:145], v[182:185], v[110:113]
	s_waitcnt lgkmcnt(1)
	v_mfma_f32_16x16x32_bf16 v[106:109], v[134:137], v[190:193], v[106:109]
	v_mfma_f32_16x16x32_bf16 v[102:105], v[142:145], v[190:193], v[102:105]
	v_mfma_f32_16x16x32_bf16 v[130:133], v[138:141], v[170:173], v[130:133]
	v_mfma_f32_16x16x32_bf16 v[126:129], v[146:149], v[170:173], v[126:129]
	v_mfma_f32_16x16x32_bf16 v[122:125], v[138:141], v[178:181], v[122:125]
	v_mfma_f32_16x16x32_bf16 v[118:121], v[146:149], v[178:181], v[118:121]
	v_mfma_f32_16x16x32_bf16 v[114:117], v[138:141], v[186:189], v[114:117]
	v_mfma_f32_16x16x32_bf16 v[110:113], v[146:149], v[186:189], v[110:113]
	s_waitcnt lgkmcnt(0)
	v_mfma_f32_16x16x32_bf16 v[106:109], v[138:141], v[194:197], v[106:109]
	v_mfma_f32_16x16x32_bf16 v[102:105], v[146:149], v[194:197], v[102:105]
	s_setprio 0
	s_setprio 1
	v_mfma_f32_16x16x32_bf16 v[98:101], v[150:153], v[166:169], v[98:101]
	v_mfma_f32_16x16x32_bf16 v[94:97], v[158:161], v[166:169], v[94:97]
	v_mfma_f32_16x16x32_bf16 v[90:93], v[150:153], v[174:177], v[90:93]
	v_mfma_f32_16x16x32_bf16 v[86:89], v[158:161], v[174:177], v[86:89]
	v_mfma_f32_16x16x32_bf16 v[82:85], v[150:153], v[182:185], v[82:85]
	v_mfma_f32_16x16x32_bf16 v[78:81], v[158:161], v[182:185], v[78:81]
	v_mfma_f32_16x16x32_bf16 v[74:77], v[150:153], v[190:193], v[74:77]
	v_mfma_f32_16x16x32_bf16 v[70:73], v[158:161], v[190:193], v[70:73]
	v_mfma_f32_16x16x32_bf16 v[98:101], v[154:157], v[170:173], v[98:101]
	v_mfma_f32_16x16x32_bf16 v[94:97], v[162:165], v[170:173], v[94:97]
	v_mfma_f32_16x16x32_bf16 v[90:93], v[154:157], v[178:181], v[90:93]
	v_mfma_f32_16x16x32_bf16 v[86:89], v[162:165], v[178:181], v[86:89]
	v_mfma_f32_16x16x32_bf16 v[82:85], v[154:157], v[186:189], v[82:85]
	v_mfma_f32_16x16x32_bf16 v[78:81], v[162:165], v[186:189], v[78:81]
	v_mfma_f32_16x16x32_bf16 v[74:77], v[154:157], v[194:197], v[74:77]
	v_mfma_f32_16x16x32_bf16 v[70:73], v[162:165], v[194:197], v[70:73]
	s_setprio 0
	s_barrier
	ds_read_b128 v[166:169], v234 offset:49152
	ds_read_b128 v[170:173], v234 offset:50176
	ds_read_b128 v[174:177], v234 offset:51200
	ds_read_b128 v[178:181], v234 offset:52224
	ds_read_b128 v[182:185], v234 offset:53248
	ds_read_b128 v[186:189], v234 offset:54272
	ds_read_b128 v[190:193], v234 offset:55296
	ds_read_b128 v[194:197], v234 offset:56320
	s_add_u32 s28, s14, 0x80
	s_addc_u32 s29, s15, 0
	s_mov_b32 m0, s50
	s_nop 0
	global_load_lds_dwordx4 v238, s[28:29]
	s_add_u32 s14, s14, 0x40080
	s_mov_b32 m0, s51
	s_nop 0
	global_load_lds_dwordx4 v240, s[28:29]
	s_addc_u32 s15, s15, 0
	s_mov_b32 m0, s54
	s_nop 0
	global_load_lds_dwordx4 v238, s[14:15]
	s_nop 0
	s_mov_b32 m0, s55
	s_nop 0
	global_load_lds_dwordx4 v240, s[14:15]
	s_nop 0
	s_mov_b32 m0, s26
	s_nop 0
	global_load_lds_dwordx4 v1, s[10:11]
	s_nop 0
	s_mov_b32 m0, s27
	s_nop 0
	global_load_lds_dwordx4 v239, s[10:11]
	s_waitcnt vmcnt(8)
	s_waitcnt lgkmcnt(0)
	s_barrier
	s_setprio 1
	s_waitcnt lgkmcnt(7)
	v_mfma_f32_16x16x32_bf16 v[66:69], v[134:137], v[166:169], v[66:69]
	v_mfma_f32_16x16x32_bf16 v[62:65], v[142:145], v[166:169], v[62:65]
	s_waitcnt lgkmcnt(5)
	v_mfma_f32_16x16x32_bf16 v[58:61], v[134:137], v[174:177], v[58:61]
	v_mfma_f32_16x16x32_bf16 v[54:57], v[142:145], v[174:177], v[54:57]
	s_waitcnt lgkmcnt(3)
	v_mfma_f32_16x16x32_bf16 v[50:53], v[134:137], v[182:185], v[50:53]
	v_mfma_f32_16x16x32_bf16 v[46:49], v[142:145], v[182:185], v[46:49]
	s_waitcnt lgkmcnt(1)
	v_mfma_f32_16x16x32_bf16 v[42:45], v[134:137], v[190:193], v[42:45]
	v_mfma_f32_16x16x32_bf16 v[38:41], v[142:145], v[190:193], v[38:41]
	v_mfma_f32_16x16x32_bf16 v[66:69], v[138:141], v[170:173], v[66:69]
	v_mfma_f32_16x16x32_bf16 v[62:65], v[146:149], v[170:173], v[62:65]
	v_mfma_f32_16x16x32_bf16 v[58:61], v[138:141], v[178:181], v[58:61]
	v_mfma_f32_16x16x32_bf16 v[54:57], v[146:149], v[178:181], v[54:57]
	v_mfma_f32_16x16x32_bf16 v[50:53], v[138:141], v[186:189], v[50:53]
	v_mfma_f32_16x16x32_bf16 v[46:49], v[146:149], v[186:189], v[46:49]
	s_waitcnt lgkmcnt(0)
	v_mfma_f32_16x16x32_bf16 v[42:45], v[138:141], v[194:197], v[42:45]
	v_mfma_f32_16x16x32_bf16 v[38:41], v[146:149], v[194:197], v[38:41]
	s_setprio 0
	s_setprio 1
	v_mfma_f32_16x16x32_bf16 v[34:37], v[150:153], v[166:169], v[34:37]
	v_mfma_f32_16x16x32_bf16 v[30:33], v[158:161], v[166:169], v[30:33]
	v_mfma_f32_16x16x32_bf16 v[26:29], v[150:153], v[174:177], v[26:29]
	v_mfma_f32_16x16x32_bf16 v[20:23], v[158:161], v[174:177], v[22:25]
	v_mfma_f32_16x16x32_bf16 v[16:19], v[150:153], v[182:185], v[16:19]
	v_mfma_f32_16x16x32_bf16 v[10:13], v[158:161], v[182:185], v[10:13]
	v_mfma_f32_16x16x32_bf16 v[6:9], v[150:153], v[190:193], v[6:9]
	v_mfma_f32_16x16x32_bf16 v[2:5], v[158:161], v[190:193], v[2:5]
	v_mfma_f32_16x16x32_bf16 v[34:37], v[154:157], v[170:173], v[34:37]
	v_mfma_f32_16x16x32_bf16 v[30:33], v[162:165], v[170:173], v[30:33]
	v_mfma_f32_16x16x32_bf16 v[26:29], v[154:157], v[178:181], v[26:29]
	v_mfma_f32_16x16x32_bf16 v[22:25], v[162:165], v[178:181], v[20:23]
	v_mfma_f32_16x16x32_bf16 v[18:21], v[154:157], v[186:189], v[16:19]
	v_mfma_f32_16x16x32_bf16 v[10:13], v[162:165], v[186:189], v[10:13]
	v_mfma_f32_16x16x32_bf16 v[6:9], v[154:157], v[194:197], v[6:9]
	v_mfma_f32_16x16x32_bf16 v[2:5], v[162:165], v[194:197], v[2:5]
	s_setprio 0
	s_barrier
	s_add_i32 s13, s13, 2
	s_add_u32 s38, s38, 0x100
	s_addc_u32 s39, s39, 0
	s_cmp_gt_u32 s13, 13
	s_cbranch_scc1 .Lkexit_e
	.p2align	6
.LBB0_1774:
	s_add_u32 s17, s48, s38
	s_addc_u32 s29, s49, s39
	s_add_u32 s10, s17, 0x100
	v_add_u32_e32 v14, 0x10000, v249
	s_addc_u32 s11, s29, 0
	ds_read_b128 v[134:137], v14
	ds_read_b128 v[138:141], v14 offset:1024
	ds_read_b128 v[142:145], v14 offset:2048
	ds_read_b128 v[146:149], v14 offset:3072
	v_add_u32_e32 v14, 0x14000, v249
	s_add_u32 s14, s20, s38
	ds_read_b128 v[150:153], v14
	ds_read_b128 v[154:157], v14 offset:1024
	ds_read_b128 v[158:161], v14 offset:2048
	ds_read_b128 v[162:165], v14 offset:3072
	s_addc_u32 s15, s21, s39
	s_add_u32 s14, s14, 0x100
	s_addc_u32 s15, s15, 0
	s_cmp_eq_u32 s13, 12
	s_cselect_b32 s40, s5, s10
	s_cselect_b32 s41, s4, s11
	s_cselect_b32 s14, s12, s14
	s_cselect_b32 s15, s9, s15
	s_add_u32 s10, s40, 0x80
	s_addc_u32 s11, s41, 0
	ds_read_b128 v[166:169], v234
	ds_read_b128 v[170:173], v234 offset:1024
	ds_read_b128 v[174:177], v234 offset:2048
	ds_read_b128 v[178:181], v234 offset:3072
	ds_read_b128 v[182:185], v234 offset:4096
	ds_read_b128 v[186:189], v234 offset:5120
	ds_read_b128 v[190:193], v234 offset:6144
	ds_read_b128 v[194:197], v234 offset:7168
	s_add_u32 s28, s17, 0x40080
	s_addc_u32 s29, s29, 0
	s_mov_b32 m0, s80
	s_nop 0
	global_load_lds_dwordx4 v1, s[28:29]
	s_nop 0
	s_mov_b32 m0, s81
	s_nop 0
	global_load_lds_dwordx4 v239, s[28:29]
	s_waitcnt vmcnt(8)
	s_waitcnt lgkmcnt(0)
	s_barrier
	s_setprio 1
	s_waitcnt lgkmcnt(7)
	v_mfma_f32_16x16x32_bf16 v[130:133], v[134:137], v[166:169], v[130:133]
	v_mfma_f32_16x16x32_bf16 v[126:129], v[142:145], v[166:169], v[126:129]
	s_waitcnt lgkmcnt(5)
	v_mfma_f32_16x16x32_bf16 v[122:125], v[134:137], v[174:177], v[122:125]
	v_mfma_f32_16x16x32_bf16 v[118:121], v[142:145], v[174:177], v[118:121]
	s_waitcnt lgkmcnt(3)
	v_mfma_f32_16x16x32_bf16 v[114:117], v[134:137], v[182:185], v[114:117]
	v_mfma_f32_16x16x32_bf16 v[110:113], v[142:145], v[182:185], v[110:113]
	s_waitcnt lgkmcnt(1)
	v_mfma_f32_16x16x32_bf16 v[106:109], v[134:137], v[190:193], v[106:109]
	v_mfma_f32_16x16x32_bf16 v[102:105], v[142:145], v[190:193], v[102:105]
	v_mfma_f32_16x16x32_bf16 v[130:133], v[138:141], v[170:173], v[130:133]
	v_mfma_f32_16x16x32_bf16 v[126:129], v[146:149], v[170:173], v[126:129]
	v_mfma_f32_16x16x32_bf16 v[122:125], v[138:141], v[178:181], v[122:125]
	v_mfma_f32_16x16x32_bf16 v[118:121], v[146:149], v[178:181], v[118:121]
	v_mfma_f32_16x16x32_bf16 v[114:117], v[138:141], v[186:189], v[114:117]
	v_mfma_f32_16x16x32_bf16 v[110:113], v[146:149], v[186:189], v[110:113]
	s_waitcnt lgkmcnt(0)
	v_mfma_f32_16x16x32_bf16 v[106:109], v[138:141], v[194:197], v[106:109]
	v_mfma_f32_16x16x32_bf16 v[102:105], v[146:149], v[194:197], v[102:105]
	s_setprio 0
	s_setprio 1
	v_mfma_f32_16x16x32_bf16 v[98:101], v[150:153], v[166:169], v[98:101]
	v_mfma_f32_16x16x32_bf16 v[94:97], v[158:161], v[166:169], v[94:97]
	v_mfma_f32_16x16x32_bf16 v[90:93], v[150:153], v[174:177], v[90:93]
	v_mfma_f32_16x16x32_bf16 v[86:89], v[158:161], v[174:177], v[86:89]
	v_mfma_f32_16x16x32_bf16 v[82:85], v[150:153], v[182:185], v[82:85]
	v_mfma_f32_16x16x32_bf16 v[78:81], v[158:161], v[182:185], v[78:81]
	v_mfma_f32_16x16x32_bf16 v[74:77], v[150:153], v[190:193], v[74:77]
	v_mfma_f32_16x16x32_bf16 v[70:73], v[158:161], v[190:193], v[70:73]
	v_mfma_f32_16x16x32_bf16 v[98:101], v[154:157], v[170:173], v[98:101]
	v_mfma_f32_16x16x32_bf16 v[94:97], v[162:165], v[170:173], v[94:97]
	v_mfma_f32_16x16x32_bf16 v[90:93], v[154:157], v[178:181], v[90:93]
	v_mfma_f32_16x16x32_bf16 v[86:89], v[162:165], v[178:181], v[86:89]
	v_mfma_f32_16x16x32_bf16 v[82:85], v[154:157], v[186:189], v[82:85]
	v_mfma_f32_16x16x32_bf16 v[78:81], v[162:165], v[186:189], v[78:81]
	v_mfma_f32_16x16x32_bf16 v[74:77], v[154:157], v[194:197], v[74:77]
	v_mfma_f32_16x16x32_bf16 v[70:73], v[162:165], v[194:197], v[70:73]
	s_setprio 0
	s_barrier
	ds_read_b128 v[166:169], v234 offset:16384
	ds_read_b128 v[170:173], v234 offset:17408
	ds_read_b128 v[174:177], v234 offset:18432
	ds_read_b128 v[178:181], v234 offset:19456
	ds_read_b128 v[182:185], v234 offset:20480
	ds_read_b128 v[186:189], v234 offset:21504
	ds_read_b128 v[190:193], v234 offset:22528
	ds_read_b128 v[194:197], v234 offset:23552
	s_mov_b32 m0, s47
	s_nop 0
	global_load_lds_dwordx4 v238, s[14:15]
	s_add_u32 s28, s14, 0x40000
	s_mov_b32 m0, s79
	s_nop 0
	global_load_lds_dwordx4 v240, s[14:15]
	s_addc_u32 s29, s15, 0
	s_mov_b32 m0, s78
	s_nop 0
	global_load_lds_dwordx4 v238, s[28:29]
	s_nop 0
	s_mov_b32 m0, s56
	s_nop 0
	global_load_lds_dwordx4 v240, s[28:29]
	s_nop 0
	s_mov_b32 m0, s45
	s_nop 0
	global_load_lds_dwordx4 v1, s[40:41]
	s_nop 0
	s_mov_b32 m0, s57
	s_nop 0
	global_load_lds_dwordx4 v239, s[40:41]
	s_waitcnt vmcnt(8)
	s_waitcnt lgkmcnt(0)
	s_barrier
	s_setprio 1
	s_waitcnt lgkmcnt(7)
	v_mfma_f32_16x16x32_bf16 v[66:69], v[134:137], v[166:169], v[66:69]
	v_mfma_f32_16x16x32_bf16 v[62:65], v[142:145], v[166:169], v[62:65]
	s_waitcnt lgkmcnt(5)
	v_mfma_f32_16x16x32_bf16 v[58:61], v[134:137], v[174:177], v[58:61]
	v_mfma_f32_16x16x32_bf16 v[54:57], v[142:145], v[174:177], v[54:57]
	s_waitcnt lgkmcnt(3)
	v_mfma_f32_16x16x32_bf16 v[50:53], v[134:137], v[182:185], v[50:53]
	v_mfma_f32_16x16x32_bf16 v[46:49], v[142:145], v[182:185], v[46:49]
	s_waitcnt lgkmcnt(1)
	v_mfma_f32_16x16x32_bf16 v[42:45], v[134:137], v[190:193], v[42:45]
	v_mfma_f32_16x16x32_bf16 v[38:41], v[142:145], v[190:193], v[38:41]
	v_mfma_f32_16x16x32_bf16 v[66:69], v[138:141], v[170:173], v[66:69]
	v_mfma_f32_16x16x32_bf16 v[62:65], v[146:149], v[170:173], v[62:65]
	v_mfma_f32_16x16x32_bf16 v[58:61], v[138:141], v[178:181], v[58:61]
	v_mfma_f32_16x16x32_bf16 v[54:57], v[146:149], v[178:181], v[54:57]
	v_mfma_f32_16x16x32_bf16 v[50:53], v[138:141], v[186:189], v[50:53]
	v_mfma_f32_16x16x32_bf16 v[46:49], v[146:149], v[186:189], v[46:49]
	s_waitcnt lgkmcnt(0)
	v_mfma_f32_16x16x32_bf16 v[42:45], v[138:141], v[194:197], v[42:45]
	v_mfma_f32_16x16x32_bf16 v[38:41], v[146:149], v[194:197], v[38:41]
	s_setprio 0
	s_setprio 1
	v_mfma_f32_16x16x32_bf16 v[34:37], v[150:153], v[166:169], v[34:37]
	v_mfma_f32_16x16x32_bf16 v[30:33], v[158:161], v[166:169], v[30:33]
	v_mfma_f32_16x16x32_bf16 v[26:29], v[150:153], v[174:177], v[26:29]
	v_mfma_f32_16x16x32_bf16 v[22:25], v[158:161], v[174:177], v[22:25]
	v_mfma_f32_16x16x32_bf16 v[16:19], v[150:153], v[182:185], v[18:21]
	v_mfma_f32_16x16x32_bf16 v[10:13], v[158:161], v[182:185], v[10:13]
	v_mfma_f32_16x16x32_bf16 v[6:9], v[150:153], v[190:193], v[6:9]
	v_mfma_f32_16x16x32_bf16 v[2:5], v[158:161], v[190:193], v[2:5]
	v_mfma_f32_16x16x32_bf16 v[34:37], v[154:157], v[170:173], v[34:37]
	v_mfma_f32_16x16x32_bf16 v[30:33], v[162:165], v[170:173], v[30:33]
	v_mfma_f32_16x16x32_bf16 v[26:29], v[154:157], v[178:181], v[26:29]
	v_mfma_f32_16x16x32_bf16 v[22:25], v[162:165], v[178:181], v[22:25]
	v_mfma_f32_16x16x32_bf16 v[16:19], v[154:157], v[186:189], v[16:19]
	v_mfma_f32_16x16x32_bf16 v[10:13], v[162:165], v[186:189], v[10:13]
	v_mfma_f32_16x16x32_bf16 v[6:9], v[154:157], v[194:197], v[6:9]
	v_mfma_f32_16x16x32_bf16 v[2:5], v[162:165], v[194:197], v[2:5]
	s_setprio 0
	s_barrier
	v_add_u32_e32 v14, 0x18000, v249
	ds_read_b128 v[134:137], v14
	ds_read_b128 v[138:141], v14 offset:1024
	ds_read_b128 v[142:145], v14 offset:2048
	ds_read_b128 v[146:149], v14 offset:3072
	v_add_u32_e32 v14, 0x1c000, v249
	ds_read_b128 v[150:153], v14
	ds_read_b128 v[154:157], v14 offset:1024
	ds_read_b128 v[158:161], v14 offset:2048
	ds_read_b128 v[162:165], v14 offset:3072
	ds_read_b128 v[166:169], v234 offset:32768
	ds_read_b128 v[170:173], v234 offset:33792
	ds_read_b128 v[174:177], v234 offset:34816
	ds_read_b128 v[178:181], v234 offset:35840
	ds_read_b128 v[182:185], v234 offset:36864
	ds_read_b128 v[186:189], v234 offset:37888
	ds_read_b128 v[190:193], v234 offset:38912
	ds_read_b128 v[194:197], v234 offset:39936
	s_add_u32 s28, s40, 0x40000
	s_addc_u32 s29, s41, 0
	s_mov_b32 m0, s76
	s_nop 0
	global_load_lds_dwordx4 v1, s[28:29]
	s_nop 0
	s_mov_b32 m0, s77
	s_nop 0
	global_load_lds_dwordx4 v239, s[28:29]
	s_waitcnt vmcnt(8)
	s_waitcnt lgkmcnt(0)
	s_barrier
	s_setprio 1
	s_waitcnt lgkmcnt(7)
	v_mfma_f32_16x16x32_bf16 v[130:133], v[134:137], v[166:169], v[130:133]
	v_mfma_f32_16x16x32_bf16 v[126:129], v[142:145], v[166:169], v[126:129]
	s_waitcnt lgkmcnt(5)
	v_mfma_f32_16x16x32_bf16 v[122:125], v[134:137], v[174:177], v[122:125]
	v_mfma_f32_16x16x32_bf16 v[118:121], v[142:145], v[174:177], v[118:121]
	s_waitcnt lgkmcnt(3)
	v_mfma_f32_16x16x32_bf16 v[114:117], v[134:137], v[182:185], v[114:117]
	v_mfma_f32_16x16x32_bf16 v[110:113], v[142:145], v[182:185], v[110:113]
	s_waitcnt lgkmcnt(1)
	v_mfma_f32_16x16x32_bf16 v[106:109], v[134:137], v[190:193], v[106:109]
	v_mfma_f32_16x16x32_bf16 v[102:105], v[142:145], v[190:193], v[102:105]
	v_mfma_f32_16x16x32_bf16 v[130:133], v[138:141], v[170:173], v[130:133]
	v_mfma_f32_16x16x32_bf16 v[126:129], v[146:149], v[170:173], v[126:129]
	v_mfma_f32_16x16x32_bf16 v[122:125], v[138:141], v[178:181], v[122:125]
	v_mfma_f32_16x16x32_bf16 v[118:121], v[146:149], v[178:181], v[118:121]
	v_mfma_f32_16x16x32_bf16 v[114:117], v[138:141], v[186:189], v[114:117]
	v_mfma_f32_16x16x32_bf16 v[110:113], v[146:149], v[186:189], v[110:113]
	s_waitcnt lgkmcnt(0)
	v_mfma_f32_16x16x32_bf16 v[106:109], v[138:141], v[194:197], v[106:109]
	v_mfma_f32_16x16x32_bf16 v[102:105], v[146:149], v[194:197], v[102:105]
	s_setprio 0
	s_setprio 1
	v_mfma_f32_16x16x32_bf16 v[98:101], v[150:153], v[166:169], v[98:101]
	v_mfma_f32_16x16x32_bf16 v[94:97], v[158:161], v[166:169], v[94:97]
	v_mfma_f32_16x16x32_bf16 v[90:93], v[150:153], v[174:177], v[90:93]
	v_mfma_f32_16x16x32_bf16 v[86:89], v[158:161], v[174:177], v[86:89]
	v_mfma_f32_16x16x32_bf16 v[82:85], v[150:153], v[182:185], v[82:85]
	v_mfma_f32_16x16x32_bf16 v[78:81], v[158:161], v[182:185], v[78:81]
	v_mfma_f32_16x16x32_bf16 v[74:77], v[150:153], v[190:193], v[74:77]
	v_mfma_f32_16x16x32_bf16 v[70:73], v[158:161], v[190:193], v[70:73]
	v_mfma_f32_16x16x32_bf16 v[98:101], v[154:157], v[170:173], v[98:101]
	v_mfma_f32_16x16x32_bf16 v[94:97], v[162:165], v[170:173], v[94:97]
	v_mfma_f32_16x16x32_bf16 v[90:93], v[154:157], v[178:181], v[90:93]
	v_mfma_f32_16x16x32_bf16 v[86:89], v[162:165], v[178:181], v[86:89]
	v_mfma_f32_16x16x32_bf16 v[82:85], v[154:157], v[186:189], v[82:85]
	v_mfma_f32_16x16x32_bf16 v[78:81], v[162:165], v[186:189], v[78:81]
	v_mfma_f32_16x16x32_bf16 v[74:77], v[154:157], v[194:197], v[74:77]
	v_mfma_f32_16x16x32_bf16 v[70:73], v[162:165], v[194:197], v[70:73]
	s_setprio 0
	s_barrier
	ds_read_b128 v[166:169], v234 offset:49152
	ds_read_b128 v[170:173], v234 offset:50176
	ds_read_b128 v[174:177], v234 offset:51200
	ds_read_b128 v[178:181], v234 offset:52224
	ds_read_b128 v[182:185], v234 offset:53248
	ds_read_b128 v[186:189], v234 offset:54272
	ds_read_b128 v[190:193], v234 offset:55296
	ds_read_b128 v[194:197], v234 offset:56320
	s_add_u32 s28, s14, 0x80
	s_addc_u32 s29, s15, 0
	s_mov_b32 m0, s50
	s_nop 0
	global_load_lds_dwordx4 v238, s[28:29]
	s_add_u32 s14, s14, 0x40080
	s_mov_b32 m0, s51
	s_nop 0
	global_load_lds_dwordx4 v240, s[28:29]
	s_addc_u32 s15, s15, 0
	s_mov_b32 m0, s54
	s_nop 0
	global_load_lds_dwordx4 v238, s[14:15]
	s_nop 0
	s_mov_b32 m0, s55
	s_nop 0
	global_load_lds_dwordx4 v240, s[14:15]
	s_nop 0
	s_mov_b32 m0, s26
	s_nop 0
	global_load_lds_dwordx4 v1, s[10:11]
	s_nop 0
	s_mov_b32 m0, s27
	s_nop 0
	global_load_lds_dwordx4 v239, s[10:11]
	s_waitcnt vmcnt(8)
	s_waitcnt lgkmcnt(0)
	s_barrier
	s_setprio 1
	s_waitcnt lgkmcnt(7)
	v_mfma_f32_16x16x32_bf16 v[66:69], v[134:137], v[166:169], v[66:69]
	v_mfma_f32_16x16x32_bf16 v[62:65], v[142:145], v[166:169], v[62:65]
	s_waitcnt lgkmcnt(5)
	v_mfma_f32_16x16x32_bf16 v[58:61], v[134:137], v[174:177], v[58:61]
	v_mfma_f32_16x16x32_bf16 v[54:57], v[142:145], v[174:177], v[54:57]
	s_waitcnt lgkmcnt(3)
	v_mfma_f32_16x16x32_bf16 v[50:53], v[134:137], v[182:185], v[50:53]
	v_mfma_f32_16x16x32_bf16 v[46:49], v[142:145], v[182:185], v[46:49]
	s_waitcnt lgkmcnt(1)
	v_mfma_f32_16x16x32_bf16 v[42:45], v[134:137], v[190:193], v[42:45]
	v_mfma_f32_16x16x32_bf16 v[38:41], v[142:145], v[190:193], v[38:41]
	v_mfma_f32_16x16x32_bf16 v[66:69], v[138:141], v[170:173], v[66:69]
	v_mfma_f32_16x16x32_bf16 v[62:65], v[146:149], v[170:173], v[62:65]
	v_mfma_f32_16x16x32_bf16 v[58:61], v[138:141], v[178:181], v[58:61]
	v_mfma_f32_16x16x32_bf16 v[54:57], v[146:149], v[178:181], v[54:57]
	v_mfma_f32_16x16x32_bf16 v[50:53], v[138:141], v[186:189], v[50:53]
	v_mfma_f32_16x16x32_bf16 v[46:49], v[146:149], v[186:189], v[46:49]
	s_waitcnt lgkmcnt(0)
	v_mfma_f32_16x16x32_bf16 v[42:45], v[138:141], v[194:197], v[42:45]
	v_mfma_f32_16x16x32_bf16 v[38:41], v[146:149], v[194:197], v[38:41]
	s_setprio 0
	s_setprio 1
	v_mfma_f32_16x16x32_bf16 v[34:37], v[150:153], v[166:169], v[34:37]
	v_mfma_f32_16x16x32_bf16 v[30:33], v[158:161], v[166:169], v[30:33]
	v_mfma_f32_16x16x32_bf16 v[26:29], v[150:153], v[174:177], v[26:29]
	v_mfma_f32_16x16x32_bf16 v[20:23], v[158:161], v[174:177], v[22:25]
	v_mfma_f32_16x16x32_bf16 v[16:19], v[150:153], v[182:185], v[16:19]
	v_mfma_f32_16x16x32_bf16 v[10:13], v[158:161], v[182:185], v[10:13]
	v_mfma_f32_16x16x32_bf16 v[6:9], v[150:153], v[190:193], v[6:9]
	v_mfma_f32_16x16x32_bf16 v[2:5], v[158:161], v[190:193], v[2:5]
	v_mfma_f32_16x16x32_bf16 v[34:37], v[154:157], v[170:173], v[34:37]
	v_mfma_f32_16x16x32_bf16 v[30:33], v[162:165], v[170:173], v[30:33]
	v_mfma_f32_16x16x32_bf16 v[26:29], v[154:157], v[178:181], v[26:29]
	v_mfma_f32_16x16x32_bf16 v[22:25], v[162:165], v[178:181], v[20:23]
	v_mfma_f32_16x16x32_bf16 v[18:21], v[154:157], v[186:189], v[16:19]
	v_mfma_f32_16x16x32_bf16 v[10:13], v[162:165], v[186:189], v[10:13]
	v_mfma_f32_16x16x32_bf16 v[6:9], v[154:157], v[194:197], v[6:9]
	v_mfma_f32_16x16x32_bf16 v[2:5], v[162:165], v[194:197], v[2:5]
	s_setprio 0
	s_barrier
	s_add_i32 s13, s13, 2
	s_add_u32 s38, s38, 0x100
	s_addc_u32 s39, s39, 0
	s_cmp_gt_u32 s13, 13
	s_cbranch_scc0 .LBB0_1774
.Lkexit_e:
	v_readlane_b32 s4, v255, 21
	v_readlane_b32 s5, v255, 22
	s_and_b64 vcc, exec, s[4:5]
	s_cbranch_vccz .LBB0_1777
	s_barrier
